# plus: attention task prologue loads the four raw-Q pieces together with counted waits instead of four drained round trips
# baseline (speedup 1.0000x reference)
; DI float bflo(unsigned u) { return __uint_as_float(u << 16); }
; DI float bfhi(unsigned u) { return __uint_as_float(u & 0xffff0000u); }
; DI float shx(float v, int o, int lane) { return __int_as_float(__builtin_amdgcn_ds_bpermute((lane ^ o) << 2, __float_as_int(v))); }
; DI void phase_attn(const Params& p, int j, float lam_init, bool last, unsigned char* shm, int wv, int slot) {
;     ...
;     DMA_TILE(kt0, 0, 0);
;     if (1 < nkt) DMA_TILE(kt0 + 1, 1, 1);
;     bf16x8 qf[4];
;     {
;       const int qtok = qrow0 + qsub * 32 + r;
;       const u16* qp = QKB + (size_t)qtok * 2048 + head * 128 + map * 64 + hh * 8;
;       float v[4][8]; float ss = 0.f;
; #pragma unroll
;       for (int kk = 0; kk < 4; ++kk) {
;         uint4 u = *(const uint4*)(qp + kk * 16);
;         v[kk][0] = bflo(u.x); v[kk][1] = bfhi(u.x); v[kk][2] = bflo(u.y); v[kk][3] = bfhi(u.y);
;         v[kk][4] = bflo(u.z); v[kk][5] = bfhi(u.z); v[kk][6] = bflo(u.w); v[kk][7] = bfhi(u.w);
;       }
; #pragma unroll
;       for (int kk = 0; kk < 4; ++kk)
; #pragma unroll
;         for (int jq = 0; jq < 8; ++jq) ss += v[kk][jq] * v[kk][jq];
;       ss += shx(ss, 32, lane);
;       const float rinv = rsqrtf(ss * (1.f / 64.f) + 1e-6f);
.LBB0_532:
	s_lshl_b32 s12, s96, 7
	v_add_u32_e32 v2, s13, v121
	s_and_b32 s12, s21, s12
	s_and_b32 s1, s1, 7
	s_lshl_b32 s21, s17, 3
	v_ashrrev_i32_e32 v3, 31, v2
	s_or_b32 s21, s21, s1
	v_lshlrev_b64 v[2:3], 12, v[2:3]
	v_mov_b32_e32 v0, 0x90000
	v_lshl_add_u64 v[2:3], s[92:93], 0, v[2:3]
	s_lshl_b32 s10, s1, 8
	v_mad_i64_i32 v[4:5], s[26:27], s21, v0, v[118:119]
	s_mov_b32 s21, s11
	v_lshl_add_u64 v[2:3], v[2:3], 0, s[10:11]
	v_lshl_add_u64 v[4:5], s[20:21], 1, v[4:5]
	v_lshlrev_b32_e32 v0, 1, v116
	s_lshl_b32 s22, s1, 7
	v_lshl_add_u64 v[6:7], v[4:5], 0, v[0:1]
	v_lshl_add_u64 v[2:3], v[2:3], 0, v[0:1]
	s_mov_b64 s[20:21], 0x48000
	v_readfirstlane_b32 s1, v153
	v_add_u32_e32 v12, 0x2000, v153
	v_lshl_add_u64 v[8:9], v[2:3], 0, s[28:29]
	v_lshl_add_u64 v[4:5], v[6:7], 0, s[20:21]
	s_mov_b32 m0, s1
	s_mov_b64 s[20:21], 0x880
	v_readfirstlane_b32 s1, v12
	global_load_lds_dwordx4 v[8:9], off
	v_lshl_add_u64 v[10:11], v[2:3], 0, s[20:21]
	s_mov_b32 m0, s1
	v_readfirstlane_b32 s1, v154
	global_load_lds_dwordx4 v[10:11], off
	v_add_u32_e32 v10, 0xe000, v153
	s_mov_b32 m0, s1
	v_readfirstlane_b32 s1, v10
	s_mov_b64 s[20:21], 0x48080
	v_add_u32_e32 v14, 0x4000, v153
	global_load_lds_dwordx4 v[6:7], off
	s_mov_b32 m0, s1
	v_lshl_add_u64 v[10:11], v[6:7], 0, s[20:21]
	s_mov_b64 s[20:21], 0x40800
	v_readfirstlane_b32 s1, v14
	global_load_lds_dwordx4 v[4:5], off
	v_lshl_add_u64 v[12:13], v[2:3], 0, s[20:21]
	s_mov_b32 m0, s1
	s_mov_b64 s[20:21], 0x40880
	global_load_lds_dwordx4 v[12:13], off
	v_add_u32_e32 v12, 0x6000, v153
	v_lshl_add_u64 v[2:3], v[2:3], 0, s[20:21]
	v_readfirstlane_b32 s1, v12
	s_mov_b32 m0, s1
	v_lshl_add_u64 v[4:5], v[6:7], 0, s[38:39]
	global_load_lds_dwordx4 v[2:3], off
	v_add_u32_e32 v2, s33, v152
	s_or_b32 s12, s25, s12
	v_readfirstlane_b32 s1, v2
	v_add_u32_e32 v2, 0x2000, v2
	s_mov_b32 m0, s1
	v_readfirstlane_b32 s1, v2
	global_load_lds_dwordx4 v[4:5], off
	s_mov_b32 m0, s1
	v_mov_b32_e32 v135, v1
	global_load_lds_dwordx4 v[10:11], off
	v_add_u32_e32 v10, s12, v155
	v_ashrrev_i32_e32 v11, 31, v10
	v_lshlrev_b64 v[2:3], 12, v[10:11]
	v_lshl_add_u64 v[2:3], s[92:93], 0, v[2:3]
	v_lshl_add_u64 v[2:3], v[2:3], 0, s[10:11]
	v_lshl_add_u64 v[2:3], v[2:3], 0, v[134:135]
	v_lshlrev_b32_e32 v4, 1, v120
	v_mov_b32_e32 v5, v1
	v_lshl_add_u64 v[36:37], v[2:3], 0, v[4:5]
	global_load_dwordx4 v[2:5], v[36:37], off
	global_load_dwordx4 v[50:53], v[36:37], off offset:32
	global_load_dwordx4 v[54:57], v[36:37], off offset:64
	global_load_dwordx4 v[58:61], v[36:37], off offset:96
	s_waitcnt vmcnt(3)
	v_lshlrev_b32_e32 v12, 16, v2
	v_and_b32_e32 v13, 0xffff0000, v2
	v_lshlrev_b32_e32 v14, 16, v3
	v_and_b32_e32 v15, 0xffff0000, v3
	v_lshlrev_b32_e32 v16, 16, v4
	v_and_b32_e32 v17, 0xffff0000, v4
	v_lshlrev_b32_e32 v18, 16, v5
	v_and_b32_e32 v19, 0xffff0000, v5
	v_pk_mul_f32 v[84:85], v[12:13], v[12:13]
	v_pk_mul_f32 v[80:81], v[14:15], v[14:15]
	v_add_f32_e32 v11, v84, v85
	v_add_f32_e32 v11, v11, v80
	v_pk_mul_f32 v[48:49], v[16:17], v[16:17]
	v_add_f32_e32 v11, v81, v11
	v_add_f32_e32 v11, v48, v11
	v_pk_mul_f32 v[46:47], v[18:19], v[18:19]
	v_add_f32_e32 v11, v49, v11
	v_add_f32_e32 v11, v46, v11
	v_add_f32_e32 v11, v47, v11
	s_waitcnt vmcnt(2)
	v_lshlrev_b32_e32 v20, 16, v50
	v_and_b32_e32 v21, 0xffff0000, v50
	v_lshlrev_b32_e32 v22, 16, v51
	v_and_b32_e32 v23, 0xffff0000, v51
	v_lshlrev_b32_e32 v24, 16, v52
	v_and_b32_e32 v25, 0xffff0000, v52
	v_lshlrev_b32_e32 v26, 16, v53
	v_and_b32_e32 v27, 0xffff0000, v53
	v_pk_mul_f32 v[86:87], v[20:21], v[20:21]
	v_pk_mul_f32 v[82:83], v[22:23], v[22:23]
	v_add_f32_e32 v11, v86, v11
	v_add_f32_e32 v11, v87, v11
	v_add_f32_e32 v11, v82, v11
	v_pk_mul_f32 v[78:79], v[24:25], v[24:25]
	v_add_f32_e32 v11, v83, v11
	v_add_f32_e32 v11, v78, v11
	v_pk_mul_f32 v[44:45], v[26:27], v[26:27]
	v_add_f32_e32 v11, v79, v11
	v_add_f32_e32 v11, v44, v11
	v_add_f32_e32 v11, v45, v11
	s_waitcnt vmcnt(1)
	v_lshlrev_b32_e32 v34, 16, v54
	v_and_b32_e32 v35, 0xffff0000, v54
	v_lshlrev_b32_e32 v32, 16, v55
	v_and_b32_e32 v33, 0xffff0000, v55
	v_lshlrev_b32_e32 v30, 16, v56
	v_and_b32_e32 v31, 0xffff0000, v56
	v_lshlrev_b32_e32 v28, 16, v57
	v_and_b32_e32 v29, 0xffff0000, v57
	v_pk_mul_f32 v[88:89], v[34:35], v[34:35]
	v_pk_mul_f32 v[92:93], v[32:33], v[32:33]
	v_add_f32_e32 v11, v88, v11
	v_add_f32_e32 v11, v89, v11
	v_add_f32_e32 v11, v92, v11
	v_pk_mul_f32 v[96:97], v[30:31], v[30:31]
	v_add_f32_e32 v11, v93, v11
	v_add_f32_e32 v11, v96, v11
	v_pk_mul_f32 v[100:101], v[28:29], v[28:29]
	v_add_f32_e32 v11, v97, v11
	v_add_f32_e32 v11, v100, v11
	v_add_f32_e32 v11, v101, v11
	s_waitcnt vmcnt(0)
	v_lshlrev_b32_e32 v42, 16, v58
	v_and_b32_e32 v43, 0xffff0000, v58
	v_lshlrev_b32_e32 v40, 16, v59
	v_and_b32_e32 v41, 0xffff0000, v59
	v_lshlrev_b32_e32 v38, 16, v60
	v_and_b32_e32 v39, 0xffff0000, v60
	v_lshlrev_b32_e32 v36, 16, v61
	v_and_b32_e32 v37, 0xffff0000, v61
	global_load_dwordx4 v[2:5], v[132:133], off offset:16
	global_load_dwordx4 v[50:53], v[132:133], off
	global_load_dwordx4 v[54:57], v[132:133], off offset:80
	global_load_dwordx4 v[58:61], v[132:133], off offset:64
	global_load_dwordx4 v[62:65], v[132:133], off offset:144
	global_load_dwordx4 v[66:69], v[132:133], off offset:128
	global_load_dwordx4 v[70:73], v[132:133], off offset:208
	global_load_dwordx4 v[74:77], v[132:133], off offset:192
	v_pk_mul_f32 v[90:91], v[42:43], v[42:43]
	v_pk_mul_f32 v[94:95], v[40:41], v[40:41]
	v_add_f32_e32 v11, v90, v11
	v_add_f32_e32 v11, v91, v11
	v_add_f32_e32 v11, v94, v11
	v_pk_mul_f32 v[98:99], v[38:39], v[38:39]
	v_add_f32_e32 v11, v95, v11
	v_add_f32_e32 v11, v98, v11
	v_pk_mul_f32 v[102:103], v[36:37], v[36:37]
	v_add_f32_e32 v11, v99, v11
	v_add_f32_e32 v11, v102, v11
	v_add_f32_e32 v11, v103, v11
	ds_bpermute_b32 v44, v117, v11
	s_waitcnt lgkmcnt(0)
; DI void phase_attn(const Params& p, int j, float lam_init, bool last, unsigned char* shm, int wv, int slot) {
;     ...
;       const float rinv = rsqrtf(ss * (1.f / 64.f) + 1e-6f);
;       const float* gq = p.in[24] + j * 64 + hh * 8;
; #pragma unroll
;       for (int kk = 0; kk < 4; ++kk) {
;         float4 g0 = *(const float4*)(gq + kk * 16), g1 = *(const float4*)(gq + kk * 16 + 4);
;         v[kk][0] *= rinv * g0.x; v[kk][1] *= rinv * g0.y; v[kk][2] *= rinv * g0.z; v[kk][3] *= rinv * g0.w;
;         v[kk][4] *= rinv * g1.x; v[kk][5] *= rinv * g1.y; v[kk][6] *= rinv * g1.z; v[kk][7] *= rinv * g1.w;
;       }
;       if (task < 4096) {
;         const int l = qtok & 2047;
;         const float prow = (float)(l >> 6), pcol = (float)(l & 63);
; #pragma unroll
;         for (int jq = 0; jq < 8; ++jq) {
;           const float invf = exp2f(-(float)(hh * 8 + jq) * 0.8304820237218406f);
;           float sn, cs;
;           __sincosf(prow * invf, &sn, &cs);
;           { const float x1 = v[0][jq], x2 = v[1][jq]; v[0][jq] = x1 * cs - x2 * sn; v[1][jq] = x1 * sn + x2 * cs; }
;           __sincosf(pcol * invf, &sn, &cs);
;           { const float x1 = v[2][jq], x2 = v[3][jq]; v[2][jq] = x1 * cs - x2 * sn; v[3][jq] = x1 * sn + x2 * cs; }
;         }
;       }
	v_add_f32_e32 v11, v11, v44
	v_fmamk_f32 v11, v11, 0x3c800000, v250
	v_cmp_gt_f32_e32 vcc, s88, v11
	v_mul_f32_e32 v44, 0x4b800000, v11
	s_nop 0
	v_cndmask_b32_e32 v11, v11, v44, vcc
	v_rsq_f32_e32 v11, v11
	s_nop 0
	v_mul_f32_e32 v44, 0x45800000, v11
	v_cndmask_b32_e32 v78, v11, v44, vcc
	s_andn2_b64 vcc, exec, s[18:19]
	s_waitcnt vmcnt(7)
	v_pk_mul_f32 v[2:3], v[2:3], v[78:79] op_sel_hi:[1,0]
	s_waitcnt vmcnt(6)
	v_pk_mul_f32 v[44:45], v[50:51], v[78:79] op_sel_hi:[1,0]
	v_pk_mul_f32 v[46:47], v[2:3], v[16:17]
	v_pk_mul_f32 v[2:3], v[4:5], v[78:79] op_sel_hi:[1,0]
	v_pk_mul_f32 v[50:51], v[44:45], v[12:13]
	v_pk_mul_f32 v[12:13], v[52:53], v[78:79] op_sel_hi:[1,0]
	v_pk_mul_f32 v[44:45], v[2:3], v[18:19]
	s_waitcnt vmcnt(4)
	v_pk_mul_f32 v[2:3], v[58:59], v[78:79] op_sel_hi:[1,0]
	v_pk_mul_f32 v[48:49], v[12:13], v[14:15]
	v_pk_mul_f32 v[14:15], v[2:3], v[20:21]
	v_pk_mul_f32 v[2:3], v[60:61], v[78:79] op_sel_hi:[1,0]
	s_waitcnt vmcnt(2)
	v_pk_mul_f32 v[16:17], v[66:67], v[78:79] op_sel_hi:[1,0]
	v_pk_mul_f32 v[12:13], v[2:3], v[22:23]
	v_pk_mul_f32 v[2:3], v[54:55], v[78:79] op_sel_hi:[1,0]
	v_pk_mul_f32 v[34:35], v[16:17], v[34:35]
	v_pk_mul_f32 v[16:17], v[68:69], v[78:79] op_sel_hi:[1,0]
	v_pk_mul_f32 v[4:5], v[2:3], v[24:25]
	v_pk_mul_f32 v[2:3], v[56:57], v[78:79] op_sel_hi:[1,0]
	v_pk_mul_f32 v[32:33], v[16:17], v[32:33]
	v_pk_mul_f32 v[16:17], v[62:63], v[78:79] op_sel_hi:[1,0]
	v_pk_mul_f32 v[2:3], v[2:3], v[26:27]
	v_pk_mul_f32 v[26:27], v[16:17], v[30:31]
	v_pk_mul_f32 v[16:17], v[64:65], v[78:79] op_sel_hi:[1,0]
	s_waitcnt vmcnt(0)
	v_pk_mul_f32 v[18:19], v[78:79], v[76:77] op_sel_hi:[0,1]
	v_pk_mul_f32 v[24:25], v[16:17], v[28:29]
	v_pk_mul_f32 v[16:17], v[74:75], v[78:79] op_sel_hi:[1,0]
	v_pk_mul_f32 v[20:21], v[78:79], v[70:71] op_sel_hi:[0,1]
	v_pk_mul_f32 v[22:23], v[78:79], v[72:73] op_sel_hi:[0,1]
	v_pk_mul_f32 v[16:17], v[16:17], v[42:43]
	v_pk_mul_f32 v[18:19], v[18:19], v[40:41]
	v_pk_mul_f32 v[20:21], v[20:21], v[38:39]
	v_pk_mul_f32 v[22:23], v[22:23], v[36:37]
	s_cbranch_vccnz .LBB0_534
	v_bfe_u32 v11, v10, 6, 5
	v_cvt_f32_ubyte0_e32 v52, v11
	v_and_b32_e32 v10, 63, v10
	v_cvt_f32_ubyte0_e32 v53, v10
	v_mul_f32_e32 v10, v160, v52
	v_mul_f32_e32 v11, 0.15915494, v10
	v_sin_f32_e32 v10, v11
	v_cos_f32_e32 v28, v11
	v_mul_f32_e32 v11, v160, v53
	v_mul_f32_e32 v11, 0.15915494, v11
	v_sin_f32_e32 v30, v11
	v_cos_f32_e32 v36, v11
	v_mul_f32_e32 v11, v161, v52
	v_mul_f32_e32 v29, 0.15915494, v11
	v_sin_f32_e32 v11, v29
	v_cos_f32_e32 v29, v29
	v_pk_mul_f32 v[38:39], v[10:11], v[14:15]
	v_pk_mul_f32 v[14:15], v[28:29], v[14:15]
	v_pk_fma_f32 v[38:39], v[28:29], v[50:51], v[38:39] neg_lo:[0,0,1] neg_hi:[0,0,1]
	v_pk_fma_f32 v[14:15], v[10:11], v[50:51], v[14:15]
	v_mul_f32_e32 v10, v161, v53
	v_mul_f32_e32 v10, 0.15915494, v10
	v_sin_f32_e32 v31, v10
	v_cos_f32_e32 v37, v10
	v_mul_f32_e32 v28, v162, v52
	v_mul_f32_e32 v29, 0.15915494, v28
	v_pk_mul_f32 v[10:11], v[30:31], v[16:17]
	v_pk_mul_f32 v[16:17], v[36:37], v[16:17]
	v_sin_f32_e32 v28, v29
	v_pk_fma_f32 v[16:17], v[30:31], v[34:35], v[16:17]
	v_cos_f32_e32 v30, v29
	v_mul_f32_e32 v29, v162, v53
	v_mul_f32_e32 v29, 0.15915494, v29
	v_pk_fma_f32 v[10:11], v[36:37], v[34:35], v[10:11] neg_lo:[0,0,1] neg_hi:[0,0,1]
	v_sin_f32_e32 v34, v29
	v_cos_f32_e32 v36, v29
	v_mul_f32_e32 v29, v163, v52
	v_mul_f32_e32 v31, 0.15915494, v29
	v_sin_f32_e32 v29, v31
	v_cos_f32_e32 v31, v31
	v_mov_b64_e32 v[50:51], v[38:39]
	v_pk_mul_f32 v[40:41], v[28:29], v[12:13]
	v_pk_mul_f32 v[12:13], v[30:31], v[12:13]
	v_pk_fma_f32 v[40:41], v[30:31], v[48:49], v[40:41] neg_lo:[0,0,1] neg_hi:[0,0,1]
	v_pk_fma_f32 v[12:13], v[28:29], v[48:49], v[12:13]
	v_mul_f32_e32 v28, v163, v53
	v_mul_f32_e32 v28, 0.15915494, v28
	v_sin_f32_e32 v35, v28
	v_cos_f32_e32 v37, v28
	v_mul_f32_e32 v30, v164, v52
	v_mul_f32_e32 v31, 0.15915494, v30
	v_pk_mul_f32 v[28:29], v[34:35], v[18:19]
	v_pk_mul_f32 v[18:19], v[36:37], v[18:19]
	v_pk_fma_f32 v[28:29], v[36:37], v[32:33], v[28:29] neg_lo:[0,0,1] neg_hi:[0,0,1]
	v_pk_fma_f32 v[18:19], v[34:35], v[32:33], v[18:19]
	v_sin_f32_e32 v30, v31
	v_cos_f32_e32 v32, v31
	v_mul_f32_e32 v31, v164, v53
	v_mul_f32_e32 v31, 0.15915494, v31
	v_sin_f32_e32 v34, v31
	v_cos_f32_e32 v36, v31
	v_mul_f32_e32 v31, v165, v52
	v_mul_f32_e32 v33, 0.15915494, v31
	v_sin_f32_e32 v31, v33
	v_cos_f32_e32 v33, v33
	v_mov_b64_e32 v[48:49], v[40:41]
	v_pk_mul_f32 v[42:43], v[30:31], v[4:5]
	v_pk_mul_f32 v[4:5], v[32:33], v[4:5]
	v_pk_fma_f32 v[42:43], v[32:33], v[46:47], v[42:43] neg_lo:[0,0,1] neg_hi:[0,0,1]
	v_pk_fma_f32 v[4:5], v[30:31], v[46:47], v[4:5]
	v_mul_f32_e32 v30, v165, v53
	v_mul_f32_e32 v30, 0.15915494, v30
	v_sin_f32_e32 v35, v30
	v_cos_f32_e32 v37, v30
	v_pk_mul_f32 v[30:31], v[34:35], v[20:21]
	v_pk_mul_f32 v[20:21], v[36:37], v[20:21]
	v_pk_fma_f32 v[30:31], v[36:37], v[26:27], v[30:31] neg_lo:[0,0,1] neg_hi:[0,0,1]
	v_pk_fma_f32 v[20:21], v[34:35], v[26:27], v[20:21]
	v_mul_f32_e32 v26, v166, v52
	v_mul_f32_e32 v27, 0.15915494, v26
	v_sin_f32_e32 v26, v27
	v_cos_f32_e32 v32, v27
	v_mul_f32_e32 v27, v166, v53
	v_mul_f32_e32 v27, 0.15915494, v27
	v_sin_f32_e32 v34, v27
	v_cos_f32_e32 v36, v27
	v_mul_f32_e32 v27, v167, v52
	v_mul_f32_e32 v33, 0.15915494, v27
	v_sin_f32_e32 v27, v33
	v_cos_f32_e32 v33, v33
	v_pk_mul_f32 v[46:47], v[26:27], v[2:3]
	v_pk_mul_f32 v[2:3], v[32:33], v[2:3]
	v_pk_fma_f32 v[46:47], v[32:33], v[44:45], v[46:47] neg_lo:[0,0,1] neg_hi:[0,0,1]
	v_pk_fma_f32 v[2:3], v[26:27], v[44:45], v[2:3]
	v_mul_f32_e32 v26, v167, v53
	v_mul_f32_e32 v26, 0.15915494, v26
	v_sin_f32_e32 v35, v26
	v_cos_f32_e32 v37, v26
	v_mov_b64_e32 v[32:33], v[28:29]
	v_mov_b64_e32 v[44:45], v[46:47]
	v_pk_mul_f32 v[26:27], v[34:35], v[22:23]
	v_pk_mul_f32 v[22:23], v[36:37], v[22:23]
	v_pk_fma_f32 v[52:53], v[36:37], v[24:25], v[26:27] neg_lo:[0,0,1] neg_hi:[0,0,1]
	v_pk_fma_f32 v[22:23], v[34:35], v[24:25], v[22:23]
	v_mov_b64_e32 v[34:35], v[10:11]
	v_mov_b64_e32 v[46:47], v[42:43]
	v_mov_b64_e32 v[26:27], v[30:31]
	v_mov_b64_e32 v[24:25], v[52:53]
